# attention main loop: K/V LDS-DMA issue moved from between the QK and PV phases into PV MFMA gaps (no m0 save/restore); plus global_* ops and deferred SSQ atomics
# baseline (speedup 1.0000x reference)
.LBB0_1062:
	s_mov_b32 s34, s18
	s_mov_b32 s1, s12
	v_lshl_add_u32 v218, s4, 1, v240
	ds_read_b64_tr_b16 v[68:69], v218 offset:24576
	ds_read_b64_tr_b16 v[70:71], v218 offset:25088
	v_add_f32_e32 v67, v98, v99
	v_add_f32_e32 v67, v100, v67
	v_add_f32_e32 v67, v101, v67
	v_add_f32_e32 v67, v102, v67
	v_add_f32_e32 v67, v103, v67
	v_cvt_pk_bf16_f32 v162, v98, v99
	v_cvt_pk_bf16_f32 v163, v100, v101
	s_waitcnt lgkmcnt(9)
	v_mfma_f32_32x32x16_bf16 v[130:145], v[206:209], v[174:177], 0
	ds_read_b64_tr_b16 v[72:73], v218 offset:28672
	ds_read_b64_tr_b16 v[74:75], v218 offset:29184
	v_add_f32_e32 v67, v104, v67
	v_add_f32_e32 v67, v105, v67
	v_add_f32_e32 v67, v106, v67
	v_add_f32_e32 v67, v107, v67
	v_cvt_pk_bf16_f32 v164, v102, v103
	v_cvt_pk_bf16_f32 v165, v104, v105
	s_waitcnt lgkmcnt(10)
	v_mfma_f32_32x32x16_bf16 v[114:129], v[202:205], v[174:177], 0
	ds_read_b64_tr_b16 v[76:77], v218 offset:25600
	ds_read_b64_tr_b16 v[78:79], v218 offset:26112
	v_add_f32_e32 v67, v108, v67
	v_add_f32_e32 v67, v109, v67
	v_add_f32_e32 v67, v110, v67
	v_add_f32_e32 v67, v111, v67
	v_cvt_pk_bf16_f32 v158, v106, v107
	v_cvt_pk_bf16_f32 v159, v108, v109
	s_waitcnt lgkmcnt(11)
	v_mfma_f32_32x32x16_bf16 v[130:145], v[198:201], v[170:173], v[130:145]
	ds_read_b64_tr_b16 v[98:99], v218 offset:29696
	ds_read_b64_tr_b16 v[100:101], v218 offset:30208
	v_add_f32_e32 v67, v112, v67
	v_add_f32_e32 v67, v113, v67
	v_add_f32_e32 v67, v82, v67
	v_add_f32_e32 v67, v83, v67
	v_cvt_pk_bf16_f32 v160, v110, v111
	v_cvt_pk_bf16_f32 v161, v112, v113
	s_waitcnt lgkmcnt(12)
	v_mfma_f32_32x32x16_bf16 v[114:129], v[194:197], v[170:173], v[114:129]
	ds_read_b64_tr_b16 v[102:103], v218 offset:26624
	ds_read_b64_tr_b16 v[104:105], v218 offset:27136
	v_add_f32_e32 v67, v84, v67
	v_add_f32_e32 v67, v85, v67
	v_add_f32_e32 v67, v86, v67
	v_add_f32_e32 v67, v87, v67
	v_cvt_pk_bf16_f32 v150, v82, v83
	v_cvt_pk_bf16_f32 v151, v84, v85
	s_waitcnt lgkmcnt(13)
	v_mfma_f32_32x32x16_bf16 v[130:145], v[190:193], v[166:169], v[130:145]
	ds_read_b64_tr_b16 v[106:107], v218 offset:30720
	ds_read_b64_tr_b16 v[108:109], v218 offset:31232
	v_add_f32_e32 v67, v88, v67
	v_add_f32_e32 v67, v89, v67
	v_add_f32_e32 v67, v90, v67
	v_add_f32_e32 v67, v91, v67
	v_cvt_pk_bf16_f32 v152, v86, v87
	v_cvt_pk_bf16_f32 v153, v88, v89
	s_waitcnt lgkmcnt(14)
	v_mfma_f32_32x32x16_bf16 v[114:129], v[186:189], v[166:169], v[114:129]
	ds_read_b64_tr_b16 v[110:111], v218 offset:27648
	ds_read_b64_tr_b16 v[112:113], v218 offset:28160
	v_add_f32_e32 v67, v92, v67
	v_add_f32_e32 v67, v93, v67
	v_add_f32_e32 v67, v94, v67
	v_add_f32_e32 v67, v95, v67
	v_cvt_pk_bf16_f32 v146, v90, v91
	v_cvt_pk_bf16_f32 v147, v92, v93
	s_waitcnt lgkmcnt(14)
	v_mfma_f32_32x32x16_bf16 v[130:145], v[182:185], v[154:157], v[130:145]
	ds_read_b64_tr_b16 v[90:91], v218 offset:31744
	ds_read_b64_tr_b16 v[92:93], v218 offset:32256
	v_add_f32_e32 v67, v96, v67
	v_add_f32_e32 v67, v97, v67
	v_add_f32_e32 v67, 0, v67
	v_cvt_pk_bf16_f32 v148, v94, v95
	v_cvt_pk_bf16_f32 v149, v96, v97
	v_mfma_f32_32x32x16_bf16 v[114:129], v[178:181], v[154:157], v[114:129]
	v_add_f32_e32 v198, v66, v67
	s_waitcnt lgkmcnt(14)
	v_mfma_f32_32x32x16_bf16 v[34:49], v[162:165], v[68:71], v[34:49]
	v_exp_f32_e32 v130, v130
	v_exp_f32_e32 v131, v131
	ds_read_b64_tr_b16 v[94:95], v218 offset:32768
	ds_read_b64_tr_b16 v[96:97], v218 offset:33280
	s_waitcnt lgkmcnt(14)
	v_mfma_f32_32x32x16_bf16 v[50:65], v[162:165], v[72:75], v[50:65]
	v_exp_f32_e32 v132, v132
	v_exp_f32_e32 v133, v133
	ds_read_b64_tr_b16 v[190:191], v218 offset:36864
	ds_read_b64_tr_b16 v[192:193], v218 offset:37376
	v_add_u32_e32 v66, s34, v238
	ds_read_b128 v[86:89], v66
	ds_read_b128 v[82:85], v66 offset:512
	s_waitcnt lgkmcnt(14)
	v_mfma_f32_32x32x16_bf16 v[34:49], v[158:161], v[76:79], v[34:49]
	v_exp_f32_e32 v134, v134
	v_exp_f32_e32 v135, v135
	ds_read_b64_tr_b16 v[194:195], v218 offset:33792
	ds_read_b64_tr_b16 v[196:197], v218 offset:34304
	ds_read_b128 v[182:185], v66 offset:2048
	ds_read_b128 v[78:81], v66 offset:2560
	v_mfma_f32_32x32x16_bf16 v[50:65], v[158:161], v[98:101], v[50:65]
	v_exp_f32_e32 v136, v136
	v_exp_f32_e32 v137, v137
	ds_read_b64_tr_b16 v[98:99], v218 offset:37888
	ds_read_b64_tr_b16 v[100:101], v218 offset:38400
	ds_read_b128 v[178:181], v66 offset:4096
	ds_read_b128 v[70:73], v66 offset:4608
	s_waitcnt lgkmcnt(14)
	v_mfma_f32_32x32x16_bf16 v[34:49], v[150:153], v[102:105], v[34:49]
	v_exp_f32_e32 v138, v138
	v_exp_f32_e32 v139, v139
	ds_read_b64_tr_b16 v[102:103], v218 offset:34816
	ds_read_b64_tr_b16 v[104:105], v218 offset:35328
	ds_read_b128 v[74:77], v66 offset:6144
	ds_read_b128 v[66:69], v66 offset:6656
	v_mfma_f32_32x32x16_bf16 v[50:65], v[150:153], v[106:109], v[50:65]
	v_exp_f32_e32 v140, v140
	v_exp_f32_e32 v141, v141
	ds_read_b64_tr_b16 v[106:107], v218 offset:38912
	ds_read_b64_tr_b16 v[108:109], v218 offset:39424
	v_mfma_f32_32x32x16_bf16 v[34:49], v[146:149], v[110:113], v[34:49]
	v_exp_f32_e32 v142, v142
	v_exp_f32_e32 v143, v143
	ds_read_b64_tr_b16 v[110:111], v218 offset:35840
	ds_read_b64_tr_b16 v[112:113], v218 offset:36352
	v_mfma_f32_32x32x16_bf16 v[50:65], v[146:149], v[90:93], v[50:65]
	v_exp_f32_e32 v144, v144
	v_exp_f32_e32 v145, v145
	ds_read_b64_tr_b16 v[90:91], v218 offset:39936
	ds_read_b64_tr_b16 v[92:93], v218 offset:40448
	s_waitcnt lgkmcnt(14)
	v_mfma_f32_32x32x16_bf16 v[2:17], v[162:165], v[94:97], v[2:17]
	v_exp_f32_e32 v114, v114
	v_exp_f32_e32 v115, v115
	v_lshl_add_u64 v[250:251], s[8:9], 0, v[216:217]
	s_add_i32 s32, s12, s96
	v_mfma_f32_32x32x16_bf16 v[18:33], v[162:165], v[190:193], v[18:33]
	v_exp_f32_e32 v116, v116
	v_exp_f32_e32 v117, v117
	v_lshl_add_u64 v[244:245], v[250:251], 0, s[22:23]
	s_mov_b32 m0, s32
	v_mfma_f32_32x32x16_bf16 v[2:17], v[158:161], v[194:197], v[2:17]
	v_exp_f32_e32 v118, v118
	v_exp_f32_e32 v119, v119
	global_load_lds_dwordx4 v[244:245], off
	v_lshl_add_u64 v[252:253], s[8:9], 0, v[214:215]
	s_lshl_b32 s32, s18, 1
	s_add_i32 s32, s32, s79
	s_waitcnt lgkmcnt(12)
	v_mfma_f32_32x32x16_bf16 v[18:33], v[158:161], v[98:101], v[18:33]
	v_exp_f32_e32 v120, v120
	v_exp_f32_e32 v121, v121
	v_lshl_add_u64 v[246:247], v[252:253], 0, s[24:25]
	s_mov_b32 m0, s32
	s_waitcnt lgkmcnt(8)
	v_mfma_f32_32x32x16_bf16 v[2:17], v[150:153], v[102:105], v[2:17]
	v_exp_f32_e32 v122, v122
	v_exp_f32_e32 v123, v123
	global_load_lds_dwordx4 v[246:247], off
	v_lshl_add_u64 v[248:249], v[252:253], 0, s[26:27]
	s_addk_i32 s32, 0x2000
	s_waitcnt lgkmcnt(4)
	v_mfma_f32_32x32x16_bf16 v[18:33], v[150:153], v[106:109], v[18:33]
	v_exp_f32_e32 v124, v124
	v_exp_f32_e32 v125, v125
	s_mov_b32 m0, s32
	s_waitcnt lgkmcnt(2)
	v_mfma_f32_32x32x16_bf16 v[2:17], v[146:149], v[110:113], v[2:17]
	v_exp_f32_e32 v126, v126
	v_exp_f32_e32 v127, v127
	global_load_lds_dwordx4 v[248:249], off
	s_waitcnt lgkmcnt(0)
	v_mfma_f32_32x32x16_bf16 v[18:33], v[146:149], v[90:93], v[18:33]
	v_exp_f32_e32 v128, v128
	v_exp_f32_e32 v129, v129
	s_waitcnt vmcnt(3) lgkmcnt(0)
	s_barrier
	s_add_i32 s4, s18, 0x2000
	s_cmpk_lg_i32 s18, 0x4000
	s_cselect_b32 s12, s4, 0
	v_lshl_add_u32 v218, s1, 1, v240
	ds_read_b64_tr_b16 v[190:191], v218 offset:24576
	ds_read_b64_tr_b16 v[192:193], v218 offset:25088
	v_mfma_f32_32x32x16_bf16 v[98:113], v[86:89], v[174:177], 0
	v_add_f32_e32 v90, v130, v131
	v_add_f32_e32 v90, v132, v90
	v_add_f32_e32 v90, v133, v90
	v_add_f32_e32 v90, v134, v90
	v_add_f32_e32 v90, v135, v90
	v_cvt_pk_bf16_f32 v162, v130, v131
	v_cvt_pk_bf16_f32 v163, v132, v133
	ds_read_b64_tr_b16 v[130:131], v218 offset:28672
	ds_read_b64_tr_b16 v[132:133], v218 offset:29184
	v_add_f32_e32 v86, v136, v90
	v_add_f32_e32 v86, v137, v86
	v_add_f32_e32 v86, v138, v86
	v_add_f32_e32 v146, v139, v86
	v_mfma_f32_32x32x16_bf16 v[82:97], v[82:85], v[174:177], 0
	v_cvt_pk_bf16_f32 v164, v134, v135
	v_cvt_pk_bf16_f32 v165, v136, v137
	ds_read_b64_tr_b16 v[134:135], v218 offset:25600
	ds_read_b64_tr_b16 v[136:137], v218 offset:26112
	v_mfma_f32_32x32x16_bf16 v[98:113], v[182:185], v[170:173], v[98:113]
	v_add_f32_e32 v146, v140, v146
	v_add_f32_e32 v146, v141, v146
	v_add_f32_e32 v146, v142, v146
	v_add_f32_e32 v146, v143, v146
	v_cvt_pk_bf16_f32 v158, v138, v139
	v_cvt_pk_bf16_f32 v159, v140, v141
	ds_read_b64_tr_b16 v[138:139], v218 offset:29696
	ds_read_b64_tr_b16 v[140:141], v218 offset:30208
	v_mfma_f32_32x32x16_bf16 v[82:97], v[78:81], v[170:173], v[82:97]
	v_add_f32_e32 v146, v144, v146
	v_add_f32_e32 v146, v145, v146
	v_add_f32_e32 v146, v114, v146
	v_add_f32_e32 v146, v115, v146
	v_cvt_pk_bf16_f32 v160, v142, v143
	v_cvt_pk_bf16_f32 v161, v144, v145
	ds_read_b64_tr_b16 v[78:79], v218 offset:26624
	ds_read_b64_tr_b16 v[80:81], v218 offset:27136
	v_mfma_f32_32x32x16_bf16 v[98:113], v[178:181], v[166:169], v[98:113]
	v_add_f32_e32 v142, v116, v146
	v_add_f32_e32 v142, v117, v142
	v_add_f32_e32 v142, v118, v142
	v_add_f32_e32 v142, v119, v142
	v_cvt_pk_bf16_f32 v150, v114, v115
	v_cvt_pk_bf16_f32 v151, v116, v117
	ds_read_b64_tr_b16 v[114:115], v218 offset:30720
	ds_read_b64_tr_b16 v[116:117], v218 offset:31232
	v_mfma_f32_32x32x16_bf16 v[82:97], v[70:73], v[166:169], v[82:97]
	v_add_f32_e32 v142, v120, v142
	v_add_f32_e32 v142, v121, v142
	v_add_f32_e32 v142, v122, v142
	v_add_f32_e32 v142, v123, v142
	v_cvt_pk_bf16_f32 v152, v118, v119
	v_cvt_pk_bf16_f32 v153, v120, v121
	ds_read_b64_tr_b16 v[70:71], v218 offset:27648
	ds_read_b64_tr_b16 v[72:73], v218 offset:28160
	v_mfma_f32_32x32x16_bf16 v[98:113], v[74:77], v[154:157], v[98:113]
	v_add_f32_e32 v118, v124, v142
	v_add_f32_e32 v118, v125, v118
	v_add_f32_e32 v118, v126, v118
	v_add_f32_e32 v118, v127, v118
	v_cvt_pk_bf16_f32 v146, v122, v123
	v_cvt_pk_bf16_f32 v147, v124, v125
	ds_read_b64_tr_b16 v[74:75], v218 offset:31744
	ds_read_b64_tr_b16 v[76:77], v218 offset:32256
	v_mfma_f32_32x32x16_bf16 v[82:97], v[66:69], v[154:157], v[82:97]
	v_add_f32_e32 v118, v128, v118
	v_add_f32_e32 v118, v129, v118
	v_add_f32_e32 v118, 0, v118
	v_cvt_pk_bf16_f32 v148, v126, v127
	v_cvt_pk_bf16_f32 v149, v128, v129
	v_add_f32_e32 v66, v198, v118
	s_add_i32 s10, s10, 2
	s_waitcnt lgkmcnt(14)
	v_mfma_f32_32x32x16_bf16 v[34:49], v[162:165], v[190:193], v[34:49]
	v_exp_f32_e32 v98, v98
	v_exp_f32_e32 v99, v99
	ds_read_b64_tr_b16 v[118:119], v218 offset:32768
	ds_read_b64_tr_b16 v[120:121], v218 offset:33280
	s_waitcnt lgkmcnt(14)
	v_mfma_f32_32x32x16_bf16 v[50:65], v[162:165], v[130:133], v[50:65]
	v_exp_f32_e32 v100, v100
	v_exp_f32_e32 v101, v101
	ds_read_b64_tr_b16 v[122:123], v218 offset:36864
	ds_read_b64_tr_b16 v[124:125], v218 offset:37376
	v_add_u32_e32 v67, s12, v238
	ds_read_b128 v[206:209], v67
	ds_read_b128 v[202:205], v67 offset:512
	s_waitcnt lgkmcnt(14)
	v_mfma_f32_32x32x16_bf16 v[34:49], v[158:161], v[134:137], v[34:49]
	v_exp_f32_e32 v102, v102
	v_exp_f32_e32 v103, v103
	ds_read_b64_tr_b16 v[126:127], v218 offset:33792
	ds_read_b64_tr_b16 v[128:129], v218 offset:34304
	ds_read_b128 v[198:201], v67 offset:2048
	ds_read_b128 v[194:197], v67 offset:2560
	v_mfma_f32_32x32x16_bf16 v[50:65], v[158:161], v[138:141], v[50:65]
	v_exp_f32_e32 v104, v104
	v_exp_f32_e32 v105, v105
	ds_read_b64_tr_b16 v[130:131], v218 offset:37888
	ds_read_b64_tr_b16 v[132:133], v218 offset:38400
	ds_read_b128 v[190:193], v67 offset:4096
	ds_read_b128 v[186:189], v67 offset:4608
	s_waitcnt lgkmcnt(14)
	v_mfma_f32_32x32x16_bf16 v[34:49], v[150:153], v[78:81], v[34:49]
	v_exp_f32_e32 v106, v106
	v_exp_f32_e32 v107, v107
	ds_read_b64_tr_b16 v[78:79], v218 offset:34816
	ds_read_b64_tr_b16 v[80:81], v218 offset:35328
	ds_read_b128 v[182:185], v67 offset:6144
	ds_read_b128 v[178:181], v67 offset:6656
	v_mfma_f32_32x32x16_bf16 v[50:65], v[150:153], v[114:117], v[50:65]
	v_exp_f32_e32 v108, v108
	v_exp_f32_e32 v109, v109
	ds_read_b64_tr_b16 v[114:115], v218 offset:38912
	ds_read_b64_tr_b16 v[116:117], v218 offset:39424
	v_mfma_f32_32x32x16_bf16 v[34:49], v[146:149], v[70:73], v[34:49]
	v_exp_f32_e32 v110, v110
	v_exp_f32_e32 v111, v111
	ds_read_b64_tr_b16 v[68:69], v218 offset:35840
	ds_read_b64_tr_b16 v[70:71], v218 offset:36352
	v_mfma_f32_32x32x16_bf16 v[50:65], v[146:149], v[74:77], v[50:65]
	v_exp_f32_e32 v112, v112
	v_exp_f32_e32 v113, v113
	ds_read_b64_tr_b16 v[72:73], v218 offset:39936
	ds_read_b64_tr_b16 v[74:75], v218 offset:40448
	s_waitcnt lgkmcnt(14)
	v_mfma_f32_32x32x16_bf16 v[2:17], v[162:165], v[118:121], v[2:17]
	v_exp_f32_e32 v82, v82
	v_exp_f32_e32 v83, v83
	s_add_i32 s32, s18, s96
	v_lshl_add_u64 v[244:245], v[250:251], 0, s[28:29]
	v_mfma_f32_32x32x16_bf16 v[18:33], v[162:165], v[122:125], v[18:33]
	v_exp_f32_e32 v84, v84
	v_exp_f32_e32 v85, v85
	s_mov_b32 m0, s32
	v_mfma_f32_32x32x16_bf16 v[2:17], v[158:161], v[126:129], v[2:17]
	v_exp_f32_e32 v86, v86
	v_exp_f32_e32 v87, v87
	global_load_lds_dwordx4 v[244:245], off
	s_lshl_b32 s32, s12, 1
	v_lshl_add_u64 v[246:247], v[252:253], 0, s[38:39]
	s_add_i32 s32, s32, s79
	s_waitcnt lgkmcnt(12)
	v_mfma_f32_32x32x16_bf16 v[18:33], v[158:161], v[130:133], v[18:33]
	v_exp_f32_e32 v88, v88
	v_exp_f32_e32 v89, v89
	s_mov_b32 m0, s32
	s_waitcnt lgkmcnt(8)
	v_mfma_f32_32x32x16_bf16 v[2:17], v[150:153], v[78:81], v[2:17]
	v_exp_f32_e32 v90, v90
	v_exp_f32_e32 v91, v91
	global_load_lds_dwordx4 v[246:247], off
	v_lshl_add_u64 v[248:249], v[252:253], 0, s[40:41]
	s_addk_i32 s32, 0x2000
	s_waitcnt lgkmcnt(4)
	v_mfma_f32_32x32x16_bf16 v[18:33], v[150:153], v[114:117], v[18:33]
	v_exp_f32_e32 v92, v92
	v_exp_f32_e32 v93, v93
	s_mov_b32 m0, s32
	s_waitcnt lgkmcnt(2)
	v_mfma_f32_32x32x16_bf16 v[2:17], v[146:149], v[68:71], v[2:17]
	v_exp_f32_e32 v94, v94
	v_exp_f32_e32 v95, v95
	global_load_lds_dwordx4 v[248:249], off
	s_waitcnt lgkmcnt(0)
	v_mfma_f32_32x32x16_bf16 v[18:33], v[146:149], v[72:75], v[18:33]
	v_exp_f32_e32 v96, v96
	v_exp_f32_e32 v97, v97
	s_waitcnt vmcnt(3) lgkmcnt(0)
	s_barrier
; #define WAIT_BAR(N) asm volatile("s_waitcnt vmcnt(" #N ") lgkmcnt(0)\n\ts_barrier":::"memory")
;   #define RESC() do{ if constexpr(!FIXED) if(resc){ asm volatile("s_waitcnt lgkmcnt(0)":::"memory"); \
;       _Pragma("unroll") for(int d_=0;d_<4;++d_) _Pragma("unroll") for(int r=0;r<16;++r)o[d_][r]*=wsf[crow(r,hi)]; } }while(0)
;   #define ROT() do{sl_prev=sl_cur;sl_cur=sl_next;sl_next=(sl_next==(NSLOT-1)*SLOTB)?0:sl_next+SLOTB;}while(0)
; template<int THRL,bool FIXED> __device__ __forceinline__ void attn_unit(int qb,const bf16*Q,const bf16*__restrict__ Kh,const bf16*__restrict__ Vh,bf16*O,const int*__restrict__ cid,char*shm,const int wid){
;     ...
;   for(;t+5<NT;t+=2){
;     STEP(pB0,pB1,pA0,pA1,t,true,true,true);     WAIT_BAR(3); RESC(); ROT();
;     STEP(pA0,pA1,pB0,pB1,t+1,true,true,true);   WAIT_BAR(3); RESC(); ROT();
;   }
	s_add_i32 s1, s12, 0x2000
	s_cmpk_lg_i32 s12, 0x4000
	s_cselect_b32 s18, s1, 0
	v_lshl_add_u64 v[214:215], v[214:215], 0, s[16:17]
	v_lshl_add_u64 v[216:217], v[216:217], 0, s[16:17]
	s_cmp_ge_i32 s10, s0
	s_mov_b32 s4, s34
	s_cbranch_scc0 .LBB0_1062
	s_add_i32 s0, s10, 1
	s_cmp_lt_i32 s0, s13
	v_lshlrev_b32_e32 v67, 4, v234
	s_cbranch_scc1 .LBB0_1069
